# P1: unit head (next-unit coordinates, pointer setup) moved behind the LDS reads of the peeled first load section
# speedup vs baseline: 1.0074x; 1.0012x over previous
.LBB0_325:
	v_add_u32_e32 v146, s53, v225
	v_add_u32_e32 v162, s54, v225
	ds_read_b128 v[134:137], v146
	ds_read_b128 v[138:141], v146 offset:1024
	ds_read_b128 v[142:145], v146 offset:2048
	ds_read_b128 v[146:149], v146 offset:3072
	ds_read_b128 v[150:153], v162
	ds_read_b128 v[154:157], v162 offset:1024
	ds_read_b128 v[158:161], v162 offset:2048
	ds_read_b128 v[162:165], v162 offset:3072
	ds_read_b128 v[166:169], v229
	ds_read_b128 v[170:173], v229 offset:1024
	ds_read_b128 v[174:177], v229 offset:2048
	ds_read_b128 v[178:181], v229 offset:3072
	ds_read_b128 v[182:185], v229 offset:4096
	ds_read_b128 v[186:189], v229 offset:5120
	ds_read_b128 v[190:193], v229 offset:6144
	ds_read_b128 v[194:197], v229 offset:7168
	s_add_i32 s44, s44, 1
	s_mul_i32 s6, s44, s15
	s_mul_hi_u32 s7, s44, s3
	s_add_i32 s7, s7, s6
	s_mul_i32 s6, s44, s3
	s_add_u32 s24, s6, s94
	s_addc_u32 s25, s7, s13
	v_cmp_gt_i64_e32 vcc, s[24:25], v[212:213]
	v_cmp_lt_i64_e64 s[6:7], s[24:25], v[210:211]
	s_cbranch_vccnz .LBB0_327
	s_ashr_i32 s20, s24, 31
	s_lshr_b32 s20, s20, 29
	s_add_i32 s20, s24, s20
	s_ashr_i32 s21, s20, 3
	s_and_b32 s20, s20, -8
	s_sub_i32 s20, s24, s20
	s_cmp_lt_i32 s20, 0
	s_cselect_b32 s22, s33, 0xb0
	s_mul_i32 s20, s20, s22
	s_add_i32 s20, s20, s21
	s_mul_hi_i32 s21, s20, 0x2e8ba2e9
	s_lshr_b32 s22, s21, 31
	s_ashr_i32 s21, s21, 5
	s_add_i32 s21, s21, s22
	s_lshl_b32 s22, s21, 3
	s_sub_i32 s23, 64, s22
	s_min_i32 s23, s23, 8
	s_mulk_i32 s21, 0xb0
	s_sub_i32 s21, s20, s21
	s_lshr_b32 s20, s21, 3
	s_and_b32 s21, s21, 7
	s_add_i32 s22, s22, s21
.LBB0_327:
	s_ashr_i32 s23, s22, 31
	s_lshl_b64 s[24:25], s[22:23], 19
	s_add_u32 s24, s72, s24
	s_addc_u32 s25, s73, s25
	s_and_b64 s[26:27], s[6:7], exec
	s_cselect_b32 s23, s25, s47
	s_cselect_b32 s56, s24, s46
	s_ashr_i32 s21, s20, 31
	s_lshl_b64 s[26:27], s[20:21], 19
	s_add_u32 s26, s0, s26
	s_addc_u32 s27, s1, s27
	s_and_b64 s[48:49], s[6:7], exec
	s_cselect_b32 s57, s27, s31
	s_cselect_b32 s58, s26, s30
	s_lshl_b32 s21, s28, 8
	v_add_u32_e32 v6, s21, v227
	s_add_u32 s28, s46, 0x3ff80
	v_ashrrev_i32_e32 v7, 31, v6
	s_addc_u32 s29, s47, 0
	v_lshl_add_u64 v[214:215], v[6:7], 4, s[16:17]
	s_add_u32 s59, s30, 0
	s_addc_u32 s60, s31, 0
	s_mov_b32 s61, -2
	s_add_u32 s28, s28, 0x100
	s_addc_u32 s29, s29, 0
	s_add_u32 s59, s59, 0x100
	s_addc_u32 s60, s60, 0
	s_cmp_eq_u32 s61, 12
	s_cselect_b64 s[30:31], -1, 0
	s_cbranch_scc0 .Lpeel1_332
	global_load_dwordx4 v[2:5], v[214:215], off
